# attention loop: six VOP3-encoded plain adds as VOP2 (v66 otherwise)
# speedup vs baseline: 1.0005x; 1.0005x over previous
.LBB0_1004:
	v_mfma_f32_32x32x16_bf16 v[68:83], v[246:249], v[250:253], 0
	v_mfma_f32_32x32x16_bf16 v[84:99], v[132:135], v[100:103], v[68:83]
	v_mfma_f32_32x32x16_bf16 v[68:83], v[136:139], v[100:103], v[68:83]
	v_add_u32_e32 v2, s45, v189
	ds_read_b128 v[184:187], v2 offset:96
	ds_read_b128 v[210:213], v2 offset:128
	ds_read_b128 v[214:217], v2 offset:6752
	ds_read_b128 v[218:221], v2 offset:160
	ds_read_b128 v[222:225], v2 offset:6784
	ds_read_b128 v[226:229], v2 offset:6816
	v_add_u32_e32 v2, s39, v200
	ds_read_b128 v[176:179], v2 offset:53248
	ds_read_b128 v[164:167], v2 offset:53280
	ds_read_b128 v[230:233], v2 offset:57856
	ds_read_b128 v[238:241], v2 offset:57888
	ds_read_b128 v[160:163], v2 offset:53312
	ds_read_b128 v[156:159], v2 offset:53344
	ds_read_b128 v[242:245], v2 offset:57920
	ds_read_b128 v[152:155], v2 offset:57952
	v_exp_f32_e32 v52, v52
	v_exp_f32_e32 v183, v36
	v_exp_f32_e32 v132, v53
	v_exp_f32_e32 v53, v54
	v_mfma_f32_32x32x16_bf16 v[68:83], v[144:147], v[104:107], v[68:83]
	v_exp_f32_e32 v54, v38
	v_exp_f32_e32 v36, v55
	v_exp_f32_e32 v55, v56
	v_exp_f32_e32 v56, v40
	v_mfma_f32_32x32x16_bf16 v[84:99], v[128:131], v[104:107], v[84:99]
	v_exp_f32_e32 v40, v39
	v_exp_f32_e32 v38, v57
	v_exp_f32_e32 v57, v58
	v_exp_f32_e32 v58, v41
	v_mfma_f32_32x32x16_bf16 v[68:83], v[140:143], v[108:111], v[68:83]
	v_add_u32_e32 v181, s44, v189
	ds_read_b128 v[144:147], v181
	ds_read_b128 v[172:175], v181 offset:32
	ds_read_b128 v[136:139], v181 offset:6656
	ds_read_b128 v[168:171], v181 offset:64
	ds_read_b128 v[148:151], v181 offset:6688
	ds_read_b128 v[140:143], v181 offset:6720
	v_exp_f32_e32 v2, v37
	v_mfma_f32_32x32x16_bf16 v[84:99], v[124:127], v[108:111], v[84:99]
	v_exp_f32_e32 v124, v59
	v_exp_f32_e32 v41, v60
	v_add_f32_e32 v133, v52, v183
	v_add_f32_e32 v37, v53, v54
	s_waitcnt lgkmcnt(14)
	v_mfma_f32_32x32x16_bf16 v[68:83], v[214:217], v[112:115], v[68:83]
	v_exp_f32_e32 v214, v42
	v_exp_f32_e32 v59, v44
	v_exp_f32_e32 v60, v43
	v_exp_f32_e32 v126, v61
	v_mfma_f32_32x32x16_bf16 v[84:99], v[184:187], v[112:115], v[84:99]
	v_exp_f32_e32 v61, v62
	v_exp_f32_e32 v62, v45
	v_exp_f32_e32 v128, v63
	v_exp_f32_e32 v63, v64
	v_mfma_f32_32x32x16_bf16 v[68:83], v[222:225], v[116:119], v[68:83]
	v_exp_f32_e32 v216, v48
	v_exp_f32_e32 v64, v47
	v_exp_f32_e32 v130, v65
	v_mfma_f32_32x32x16_bf16 v[84:99], v[210:213], v[116:119], v[84:99]
	v_exp_f32_e32 v65, v66
	v_exp_f32_e32 v215, v46
	v_exp_f32_e32 v185, v50
	v_mfma_f32_32x32x16_bf16 v[68:83], v[226:229], v[120:123], v[68:83]
	v_exp_f32_e32 v66, v49
	v_exp_f32_e32 v134, v67
	v_add_f32_e32 v39, v55, v56
	v_add_f32_e32 v125, v57, v214
	v_mfma_f32_32x32x16_bf16 v[84:99], v[218:221], v[120:123], v[84:99]
	v_add_f32_e32 v127, v41, v59
	v_add_f32_e32 v129, v61, v215
	v_add_f32_e32 v131, v63, v216
	v_add_f32_e32 v135, v65, v185
	v_exp_f32_e32 v184, v51
	v_cvt_pk_bf16_f32 v42, v52, v132
	v_cvt_pk_bf16_f32 v43, v53, v36
	v_cvt_pk_bf16_f32 v44, v55, v38
	v_cvt_pk_bf16_f32 v45, v57, v124
	v_cvt_pk_bf16_f32 v46, v41, v126
	v_cvt_pk_bf16_f32 v47, v61, v128
	s_waitcnt lgkmcnt(11)
	v_mfma_f32_32x32x16_bf16 v[4:19], v[42:45], v[230:233], v[4:19]
	v_cvt_pk_bf16_f32 v48, v63, v130
	v_cvt_pk_bf16_f32 v49, v65, v134
	v_cvt_pk_bf16_f32 v50, v183, v2
	v_cvt_pk_bf16_f32 v51, v54, v40
	v_cvt_pk_bf16_f32 v52, v56, v58
	v_cvt_pk_bf16_f32 v53, v214, v60
	v_mfma_f32_32x32x16_bf16 v[20:35], v[42:45], v[176:179], v[20:35]
	v_cvt_pk_bf16_f32 v54, v59, v62
	v_cvt_pk_bf16_f32 v55, v215, v64
	v_cvt_pk_bf16_f32 v56, v216, v66
	v_cvt_pk_bf16_f32 v57, v185, v184
	s_add_i32 s14, s46, 5
	s_min_u32 s14, s14, s37
	s_add_i32 s15, s46, 3
	s_min_u32 s46, s15, s37
	s_mulk_i32 s14, 0x3000
	s_add_u32 s14, s10, s14
	s_addc_u32 s15, s11, 0
	s_lshl_b32 s46, s46, 13
	s_add_u32 s46, s12, s46
	s_addc_u32 s47, s13, 0
	s_add_i32 m0, s22, s45
	s_and_b64 s[48:49], s[4:5], exec
	s_waitcnt vmcnt(3) lgkmcnt(0)
	s_barrier
	v_mfma_f32_32x32x16_bf16 v[4:19], v[46:49], v[238:241], v[4:19]
	global_load_lds_dwordx4 v190, s[14:15]
	s_cselect_b32 s15, s15, s47
	s_cselect_b32 s14, s14, s46
	s_cselect_b32 s98, s45, s39
	s_add_i32 m0, s21, s98
	s_add_i32 s98, s23, s39
	global_load_lds_dwordx4 v192, s[14:15]
	s_add_i32 m0, s98, 0xd000
	s_nop 0
	global_load_lds_dwordx4 v194, s[46:47]
	v_max3_f32 v41, v84, v68, v85
	v_max3_f32 v59, v92, v76, v93
	v_add_f32_e32 v132, v132, v2
	v_max3_f32 v41, v41, v69, v86
	v_max3_f32 v59, v59, v77, v94
	v_mfma_f32_32x32x16_bf16 v[20:35], v[46:49], v[164:167], v[20:35]
	s_nop 0
	v_max3_f32 v41, v41, v70, v87
	v_max3_f32 v41, v41, v71, v88
	v_max3_f32 v59, v59, v78, v95
	v_max3_f32 v41, v41, v72, v89
	v_max3_f32 v59, v59, v79, v96
	s_nop 0
	v_max3_f32 v41, v41, v73, v90
	v_max3_f32 v183, v41, v74, v91
	v_mfma_f32_32x32x16_bf16 v[4:19], v[50:53], v[242:245], v[4:19]
	v_add_f32_e32 v41, v132, v133
	v_max3_f32 v59, v59, v80, v97
	v_add_f32_e32 v36, v36, v40
	v_add_f32_e32 v37, v37, v41
	v_max3_f32 v59, v59, v81, v98
	v_max3_f32 v186, v59, v82, v99
	v_add_f32_e32 v59, v36, v37
	v_add_f32_e32 v36, v38, v58
	v_add_f32_e32 v37, v39, v59
	v_mfma_f32_32x32x16_bf16 v[20:35], v[50:53], v[160:163], v[20:35]
	v_add_f32_e32 v61, v36, v37
	v_add_f32_e32 v36, v124, v60
	v_add_f32_e32 v37, v125, v61
	v_add_f32_e32 v63, v36, v37
	v_add_f32_e32 v36, v126, v62
	v_add_f32_e32 v37, v127, v63
	v_add_f32_e32 v65, v36, v37
	v_add_f32_e32 v36, v128, v64
	v_add_f32_e32 v37, v129, v65
	v_mfma_f32_32x32x16_bf16 v[20:35], v[54:57], v[156:159], v[20:35]
	v_add_f32_e32 v67, v36, v37
	v_add_f32_e32 v36, v130, v66
	v_add_f32_e32 v37, v131, v67
	v_add_f32_e32 v185, v36, v37
	v_add_f32_e32 v36, v134, v184
	v_add_f32_e32 v37, v135, v185
	v_add_f32_e32 v2, v36, v37
	v_max3_f32 v36, v183, v75, v186
	v_add_f32_e32 v2, v209, v2
	v_mfma_f32_32x32x16_bf16 v[4:19], v[54:57], v[152:155], v[4:19]
	v_max3_f32 v36, v36, v83, v36
	s_nop 0
	v_mov_b32_e32 v38, v36
	s_nop 0
	s_nop 0
	v_permlane32_swap_b32_e32 v36, v38
	v_max3_f32 v36, v36, v38, v36
	s_nop 0
	v_cmp_lt_f32_e32 vcc, s56, v36
	s_cbranch_vccz .LBB0_1008
	s_nop 0
	v_add_f32_e32 v210, v180, v36
	v_cvt_pk_bf16_f32 v210, v210, v210
	v_lshlrev_b32_e32 v210, 16, v210
	v_cndmask_b32_e32 v210, v180, v210, vcc
	v_sub_f32_e32 v36, v180, v210
	v_sub_f32_e32 v186, v210, v180
	v_xor_b32_e32 v250, 0x80000000, v210
	v_min_f32_e32 v36, 0, v36
	v_lshrrev_b32_e32 v250, 16, v250
	v_exp_f32_e32 v36, v36
	v_cndmask_b32_e64 v250, 0, v250, s[2:3]
	s_and_saveexec_b64 s[14:15], s[2:3]
	ds_write_b32 v202, v36
	s_or_b64 exec, exec, s[14:15]
	v_mul_f32_e32 v2, v2, v36
	ds_read_b32 v36, v1
	ds_read_b32 v37, v1 offset:4
	ds_read_b32 v38, v1 offset:8
	ds_read_b32 v39, v1 offset:12
	ds_read_b32 v40, v1 offset:32
	ds_read_b32 v41, v1 offset:36
	ds_read_b32 v42, v1 offset:40
	ds_read_b32 v43, v1 offset:44
	ds_read_b32 v44, v1 offset:64
	ds_read_b32 v45, v1 offset:68
	ds_read_b32 v46, v1 offset:72
	ds_read_b32 v47, v1 offset:76
	ds_read_b32 v48, v1 offset:96
	ds_read_b32 v49, v1 offset:100
	ds_read_b32 v50, v1 offset:104
	ds_read_b32 v51, v1 offset:108
	s_waitcnt lgkmcnt(0)
	v_pk_mul_f32 v[20:21], v[20:21], v[36:37]
	v_pk_mul_f32 v[22:23], v[22:23], v[38:39]
	v_pk_mul_f32 v[24:25], v[24:25], v[40:41]
	v_pk_mul_f32 v[26:27], v[26:27], v[42:43]
	v_pk_mul_f32 v[28:29], v[28:29], v[44:45]
	v_pk_mul_f32 v[30:31], v[30:31], v[46:47]
	v_pk_mul_f32 v[32:33], v[32:33], v[48:49]
	v_pk_mul_f32 v[34:35], v[34:35], v[50:51]
	v_pk_mul_f32 v[4:5], v[4:5], v[36:37]
	v_pk_mul_f32 v[6:7], v[6:7], v[38:39]
	v_pk_mul_f32 v[8:9], v[8:9], v[40:41]
	v_pk_mul_f32 v[10:11], v[10:11], v[42:43]
	v_pk_mul_f32 v[12:13], v[12:13], v[44:45]
	v_pk_mul_f32 v[14:15], v[14:15], v[46:47]
	v_pk_mul_f32 v[16:17], v[16:17], v[48:49]
	v_pk_mul_f32 v[18:19], v[18:19], v[50:51]
	v_sub_f32_e32 v68, v68, v186
	v_sub_f32_e32 v69, v69, v186
	v_sub_f32_e32 v70, v70, v186
	v_sub_f32_e32 v71, v71, v186
	v_sub_f32_e32 v72, v72, v186
	v_sub_f32_e32 v73, v73, v186
	v_sub_f32_e32 v74, v74, v186
	v_sub_f32_e32 v75, v75, v186
	v_sub_f32_e32 v76, v76, v186
	v_sub_f32_e32 v77, v77, v186
	v_sub_f32_e32 v78, v78, v186
	v_sub_f32_e32 v79, v79, v186
	v_sub_f32_e32 v80, v80, v186
	v_sub_f32_e32 v81, v81, v186
	v_sub_f32_e32 v82, v82, v186
	v_sub_f32_e32 v83, v83, v186
	v_sub_f32_e32 v84, v84, v186
	v_sub_f32_e32 v85, v85, v186
	v_sub_f32_e32 v86, v86, v186
	v_sub_f32_e32 v87, v87, v186
	v_sub_f32_e32 v88, v88, v186
	v_sub_f32_e32 v89, v89, v186
	v_sub_f32_e32 v90, v90, v186
	v_sub_f32_e32 v91, v91, v186
	v_sub_f32_e32 v92, v92, v186
	v_sub_f32_e32 v93, v93, v186
	v_sub_f32_e32 v94, v94, v186
	v_sub_f32_e32 v95, v95, v186
	v_sub_f32_e32 v96, v96, v186
	v_sub_f32_e32 v97, v97, v186
	v_sub_f32_e32 v98, v98, v186
	v_sub_f32_e32 v99, v99, v186
	s_mov_b32 s56, 0x41000000
	s_branch .LBB0_1009

.LBB0_1009:
	v_mfma_f32_32x32x16_bf16 v[36:51], v[246:249], v[250:253], 0
	v_mfma_f32_32x32x16_bf16 v[52:67], v[144:147], v[100:103], v[36:51]
	v_mfma_f32_32x32x16_bf16 v[36:51], v[136:139], v[100:103], v[36:51]
	v_add_u32_e32 v255, s43, v200
	ds_read_b128 v[212:215], v181 offset:96
	ds_read_b128 v[216:219], v181 offset:128
	ds_read_b128 v[220:223], v181 offset:6752
	ds_read_b128 v[224:227], v181 offset:160
	ds_read_b128 v[228:231], v181 offset:6784
	ds_read_b128 v[238:241], v181 offset:6816
	ds_read_b128 v[160:163], v255 offset:53248
	ds_read_b128 v[164:167], v255 offset:53280
	ds_read_b128 v[184:187], v255 offset:57856
	ds_read_b128 v[180:183], v255 offset:57888
	ds_read_b128 v[156:159], v255 offset:53312
	ds_read_b128 v[152:155], v255 offset:53344
	v_add_u32_e32 v209, s41, v189
	v_mfma_f32_32x32x16_bf16 v[36:51], v[148:151], v[104:107], v[36:51]
	ds_read_b128 v[176:179], v255 offset:57920
	ds_read_b128 v[148:151], v255 offset:57952
	v_exp_f32_e32 v211, v84
	v_exp_f32_e32 v232, v68
	v_exp_f32_e32 v233, v85
	v_exp_f32_e32 v235, v69
	v_add_f32_e32 v68, v211, v232
	v_add_f32_e32 v69, v233, v235
	v_add_f32_e32 v68, v69, v68
	v_mfma_f32_32x32x16_bf16 v[52:67], v[172:175], v[104:107], v[52:67]
	v_exp_f32_e32 v173, v70
	v_exp_f32_e32 v172, v86
	v_exp_f32_e32 v174, v87
	v_exp_f32_e32 v175, v71
	v_add_f32_e32 v69, v172, v173
	v_add_f32_e32 v68, v69, v68
	v_mfma_f32_32x32x16_bf16 v[52:67], v[168:171], v[108:111], v[52:67]
	v_add_f32_e32 v69, v174, v175
	v_add_f32_e32 v168, v69, v68
	v_exp_f32_e32 v71, v88
	v_exp_f32_e32 v85, v72
	v_exp_f32_e32 v70, v89
	v_exp_f32_e32 v84, v73
	v_exp_f32_e32 v73, v90
	v_exp_f32_e32 v87, v74
	v_exp_f32_e32 v72, v91
	v_exp_f32_e32 v86, v75
	v_add_f32_e32 v68, v70, v84
	v_add_f32_e32 v69, v71, v85
	v_mfma_f32_32x32x16_bf16 v[36:51], v[140:143], v[108:111], v[36:51]
	v_add_f32_e32 v69, v69, v168
	v_add_f32_e32 v74, v68, v69
	v_add_f32_e32 v68, v72, v86
	v_add_f32_e32 v69, v73, v87
	ds_read_b128 v[132:135], v209
	ds_read_b128 v[128:131], v209 offset:32
	ds_read_b128 v[136:139], v209 offset:6656
	ds_read_b128 v[124:127], v209 offset:64
	v_add_f32_e32 v69, v69, v74
	v_add_f32_e32 v168, v68, v69
	v_exp_f32_e32 v75, v92
	v_exp_f32_e32 v89, v76
	v_exp_f32_e32 v74, v93
	v_exp_f32_e32 v88, v77
	v_exp_f32_e32 v77, v94
	s_waitcnt lgkmcnt(12)
	v_mfma_f32_32x32x16_bf16 v[36:51], v[220:223], v[112:115], v[36:51]
	v_exp_f32_e32 v91, v78
	v_exp_f32_e32 v76, v95
	v_exp_f32_e32 v90, v79
	v_add_f32_e32 v68, v74, v88
	v_add_f32_e32 v69, v75, v89
	ds_read_b128 v[144:147], v209 offset:6688
	ds_read_b128 v[140:143], v209 offset:6720
	v_mfma_f32_32x32x16_bf16 v[52:67], v[212:215], v[112:115], v[52:67]
	v_add_f32_e32 v69, v69, v168
	v_add_f32_e32 v78, v68, v69
	v_add_f32_e32 v68, v76, v90
	v_add_f32_e32 v69, v77, v91
	v_add_f32_e32 v69, v69, v78
	v_add_f32_e32 v168, v68, v69
	v_mfma_f32_32x32x16_bf16 v[36:51], v[228:231], v[116:119], v[36:51]
	v_exp_f32_e32 v79, v96
	v_exp_f32_e32 v93, v80
	v_exp_f32_e32 v78, v97
	v_exp_f32_e32 v92, v81
	v_mfma_f32_32x32x16_bf16 v[52:67], v[216:219], v[116:119], v[52:67]
	v_exp_f32_e32 v95, v98
	v_exp_f32_e32 v97, v82
	v_exp_f32_e32 v94, v99
	v_mfma_f32_32x32x16_bf16 v[36:51], v[238:241], v[120:123], v[36:51]
	v_exp_f32_e32 v96, v83
	v_add_f32_e32 v68, v78, v92
	v_add_f32_e32 v69, v79, v93
	s_nop 0
	v_add_f32_e32 v69, v69, v168
	v_add_f32_e32 v80, v68, v69
	v_add_f32_e32 v68, v94, v96
	v_add_f32_e32 v69, v95, v97
	v_mfma_f32_32x32x16_bf16 v[52:67], v[224:227], v[120:123], v[52:67]
	v_add_f32_e32 v69, v69, v80
	v_add_f32_e32 v68, v68, v69
	v_add_f32_e32 v209, v2, v68
	v_cvt_pk_bf16_f32 v68, v211, v233
	v_cvt_pk_bf16_f32 v69, v172, v174
	v_cvt_pk_bf16_f32 v70, v71, v70
	v_cvt_pk_bf16_f32 v71, v73, v72
	v_cvt_pk_bf16_f32 v80, v75, v74
	v_cvt_pk_bf16_f32 v81, v77, v76
	s_waitcnt lgkmcnt(11)
	v_mfma_f32_32x32x16_bf16 v[4:19], v[68:71], v[184:187], v[4:19]
	v_cvt_pk_bf16_f32 v82, v79, v78
	v_cvt_pk_bf16_f32 v83, v95, v94
	v_cvt_pk_bf16_f32 v76, v232, v235
	v_cvt_pk_bf16_f32 v77, v173, v175
	v_cvt_pk_bf16_f32 v78, v85, v84
	v_cvt_pk_bf16_f32 v79, v87, v86
	v_mfma_f32_32x32x16_bf16 v[20:35], v[68:71], v[160:163], v[20:35]
	v_cvt_pk_bf16_f32 v72, v89, v88
	v_cvt_pk_bf16_f32 v73, v91, v90
	v_cvt_pk_bf16_f32 v74, v93, v92
	v_cvt_pk_bf16_f32 v75, v97, v96
	s_cmp_ge_u32 s42, s36
	s_cbranch_scc1 .Lattn_exit
	s_mov_b32 s14, s41
	s_mov_b32 s15, s38
	s_mov_b32 s41, s45
	s_mov_b32 s38, s44
	s_mov_b32 s44, s40
	s_mov_b32 s40, s43
	s_mov_b32 s46, s42
	s_add_i32 s42, s46, 4
	s_min_u32 s43, s42, s37
	s_add_i32 s42, s46, 2
	s_min_u32 s45, s42, s37
	s_mulk_i32 s43, 0x3000
	s_add_u32 s48, s10, s43
	s_addc_u32 s49, s11, 0
	s_lshl_b32 s43, s45, 13
	s_add_u32 s50, s12, s43
	s_addc_u32 s51, s13, 0
	s_add_i32 m0, s22, s38
	s_and_b64 s[52:53], s[4:5], exec
	s_waitcnt vmcnt(3) lgkmcnt(0)
	s_barrier
	s_branch .LBB0_999
